# attn prefetch moved after Q waits; mLSTM: norm weights via LDS, K/V+Q prefetch hoisted, vmcnt re-derived
# speedup vs baseline: 1.0025x; 1.0025x over previous
; #define LAS __attribute__((address_space(3)))
; __device__ __forceinline__ void p2_mlstm(const Params& p, LAS unsigned char* lds) {
;     ...
;         f32x4 cacc[3][2];
; #pragma unroll
;         for (int vt = 0; vt < 3; ++vt)
; #pragma unroll
;             for (int dd = 0; dd < 2; ++dd) cacc[vt][dd] = (f32x4){0.f, 0.f, 0.f, 0.f};
;         for (int i = tid; i < (ML_G - ML_VT) / 4; i += 512) ((LAS unsigned*)(lds + ML_VT))[i] = 0u;
; #pragma unroll 1
;         for (int cc = 0; cc < 2; ++cc) {
;             const int ck = 2 * wid + cc; const int t0 = tokbase + ck * 128 + 2 * lane;
;             const float ig0 = GATES[(size_t)t0 * 8 + h], lf0 = GATES[(size_t)t0 * 8 + 4 + h], ig1 = GATES[(size_t)(t0 + 1) * 8 + h], lf1 = GATES[(size_t)(t0 + 1) * 8 + 4 + h];
;             float sc = lf0 + lf1;
; #pragma unroll
;             for (int off = 1; off < 64; off <<= 1) { const float t = __shfl_up(sc, off); if (lane >= off) sc += t; }
;             const float b1 = sc, b0 = sc - lf1;
;             const float u0 = ig0 - b0, u1 = ig1 - b1;
;             float cm = fmaxf(u0, u1);
; #pragma unroll
;             for (int off = 1; off < 64; off <<= 1) { const float t = __shfl_up(cm, off); if (lane >= off) cm = fmaxf(cm, t); }
;             float cprev = __shfl_up(cm, 1); if (lane == 0) cprev = -1e30f;
;             const int gi = ck * 128 + 2 * lane;
;             PU[gi] = u0; PU[gi + 1] = u1; PCM[gi] = fmaxf(cprev, u0); PCM[gi + 1] = cm; PB[gi] = b0; PB[gi + 1] = b1;
;             if (lane == 63) { PBT[ck] = b1; PCT[ck] = cm; }
;         }
;         __syncthreads();
;         if (tid < 128) ((LAS unsigned*)NV)[tid] = 0u;
;         if (tid == 0) {
;             float mprev = 0.f;
; #pragma unroll 1
;             for (int c = 0; c < 16; ++c) { const float mm = fmaxf(mprev, PCT[c]); MPREV[c] = mprev; MM127[c] = mm; mprev = PBT[c] + mm; }
;         }
;         u32x4 kreg[8], vreg, qfn[8];
;         const unsigned qoff = ((unsigned)(16 * wid + r) * 2048u + (unsigned)(h * 256 + 8 * q)) * 2u;
;         const unsigned koff = ((unsigned)(tid >> 5) * 2048u + 1024u + (unsigned)(h * 256) + (unsigned)(tid & 31) * 8u) * 2u;
;         const unsigned voff = ((unsigned)(tid >> 2) * 5120u + 2048u + (unsigned)(h * 256 + sl * 32) + (unsigned)(tid & 3) * 8u) * 2u;
;         const unsigned ooff = ((unsigned)(16 * wid + r) * 5120u + 3072u + (unsigned)(h * 256 + sl * 32 + 4 * q)) * 2u;
.LBB0_248:
	s_or_b64 exec, exec, s[34:35]
	s_bfe_u32 s78, s84, 0x30003
	s_lshl_b32 s1, s33, 9
	s_and_b32 s80, s1, 0x3800
	s_lshl_b32 s6, s82, 8
	s_lshl_b32 s7, s78, 5
	s_ashr_i32 s1, s0, 31
	v_writelane_b32 v254, s33, 61
	s_lshl_b32 s81, s78, 6
	v_or_b32_e32 v5, s6, v203
	s_or_b32 s33, s7, s6
	s_lshl_b64 s[34:35], s[0:1], 12
	v_lshlrev_b32_e32 v160, 1, v5
	v_or_b32_e32 v5, s6, v193
	s_add_u32 s34, s94, s34
	v_lshlrev_b32_e32 v162, 1, v5
	s_addc_u32 s35, s95, s35
	v_mov_b32_e32 v163, v4
	v_lshl_add_u64 v[6:7], s[34:35], 0, v[162:163]
	s_mov_b32 s40, 0x10000
	v_add_co_u32_e32 v44, vcc, s40, v6
	s_mov_b32 s79, 0x50000
	s_nop 0
	v_addc_co_u32_e32 v45, vcc, 0, v7, vcc
	v_add_co_u32_e32 v48, vcc, s37, v6
	global_load_dwordx4 v[8:11], v160, s[34:35] offset:64
	global_load_dwordx4 v[12:15], v160, s[34:35] offset:128
	global_load_dwordx4 v[16:19], v160, s[34:35] offset:192
	global_load_dwordx4 v[20:23], v160, s[34:35] offset:256
	global_load_dwordx4 v[24:27], v160, s[34:35] offset:320
	global_load_dwordx4 v[32:35], v160, s[34:35] offset:384
	global_load_dwordx4 v[36:39], v160, s[34:35] offset:448
	v_addc_co_u32_e32 v49, vcc, 0, v7, vcc
	v_add_co_u32_e32 v60, vcc, s79, v6
	s_mov_b32 s79, 0x70000
	s_nop 0
	v_addc_co_u32_e32 v61, vcc, 0, v7, vcc
	v_add_co_u32_e32 v6, vcc, s79, v6
	s_mul_hi_i32 s1, s0, 0x2800
	s_nop 0
	v_addc_co_u32_e32 v7, vcc, 0, v7, vcc
	s_mulk_i32 s0, 0x2800
	v_readlane_b32 vcc_lo, v254, 20
	v_or_b32_e32 v5, s33, v194
	v_or_b32_e32 v164, 0x20800, v162
	v_or_b32_e32 v168, 0x60800, v162
	v_readlane_b32 vcc_hi, v254, 21
	s_add_u32 s0, vcc_lo, s0
	global_load_dwordx4 v[28:31], v160, s[34:35]
	global_load_dwordx4 v[40:43], v162, s[34:35] offset:2048
	s_nop 0
	global_load_dwordx4 v[44:47], v[44:45], off offset:2048
	s_nop 0
	global_load_dwordx4 v[52:55], v[48:49], off offset:2048
	v_or_b32_e32 v166, 0x40800, v162
	global_load_dwordx4 v[48:51], v164, s[34:35]
	global_load_dwordx4 v[56:59], v166, s[34:35]
	s_nop 0
	global_load_dwordx4 v[60:63], v[60:61], off offset:2048
	s_nop 0
	global_load_dwordx4 v[64:67], v[6:7], off offset:2048
	v_lshlrev_b32_e32 v6, 1, v5
	s_addc_u32 s1, vcc_hi, s1
	global_load_dwordx4 v[68:71], v168, s[34:35]
	global_load_dwordx4 v[72:75], v6, s[0:1]
	s_lshl_b32 s0, s82, 5
	v_readlane_b32 s1, v254, 41
	s_add_u32 s0, s1, s0
	v_readlane_b32 s1, v254, 47
	s_addc_u32 s1, s1, 0
	s_lshl_b32 s34, s78, 2
	s_add_u32 s78, s0, s34
	s_addc_u32 s79, s1, 0
	s_lshl_b32 s0, s83, 9
	s_add_i32 s80, s80, s0
	v_or_b32_e32 v5, s33, v195
	v_mov_b32_e32 v7, v4
	s_and_b32 s0, s80, 0xfffff800
	v_lshl_add_u64 v[170:171], vcc, 0, v[6:7]
	v_lshlrev_b32_e32 v6, 2, v5
	s_ashr_i32 s1, s0, 31
	v_or_b32_e32 v5, s6, v195
	s_mov_b64 s[4:5], s[54:55]
	s_mov_b64 s[64:65], s[48:49]
	s_mov_b64 s[62:63], s[46:47]
	v_readlane_b32 s40, v254, 4
	s_or_b32 s80, s0, 0x80
	s_lshl_b64 s[34:35], s[0:1], 11
	v_or_b32_e32 v5, s7, v5
	v_readlane_b32 s6, v254, 23
	v_readlane_b32 s41, v254, 5
	v_readlane_b32 s42, v254, 6
	v_readlane_b32 s43, v254, 7
	v_readlane_b32 s7, v254, 24
	s_add_u32 s34, s6, s34
	v_readlane_b32 s52, v254, 16
	v_readlane_b32 s53, v254, 17
	s_addc_u32 s35, s7, s35
	s_mul_i32 s7, s0, 0x2800
	v_readlane_b32 s40, v254, 43
	v_lshl_add_u64 v[172:173], s[52:53], 0, v[6:7]
	global_load_dwordx4 v[100:103], v[172:173], off
	global_load_dwordx4 v[104:107], v[172:173], off offset:64
	v_lshlrev_b32_e32 v108, 2, v195
	v_add_u32_e32 v108, 0x24c00, v108
	s_waitcnt vmcnt(0)
	ds_write_b128 v108, v[100:103]
	ds_write_b128 v108, v[104:107] offset:64
	v_lshl_add_u32 v6, v5, 1, v217
	s_mul_hi_i32 s6, s0, 0x2800
	v_readlane_b32 s41, v254, 44
	s_add_u32 s0, s40, s7
	v_lshl_add_u64 v[174:175], s[34:35], 0, v[6:7]
	v_add_lshl_u32 v6, s33, v218, 1
	s_addc_u32 s1, s41, s6
	v_lshl_add_u64 v[176:177], s[0:1], 0, v[6:7]
	s_lshl_b32 s0, s82, 9
	s_or_b32 s33, s81, s0
	s_add_u32 s0, vcc_lo, s7
	v_readlane_b32 s46, v254, 10
	v_readlane_b32 s47, v254, 11
	v_readlane_b32 s48, v254, 12
	v_readlane_b32 s49, v254, 13
	v_readlane_b32 s54, v254, 18
	v_readlane_b32 s55, v254, 19
	v_add_u32_e32 v6, s33, v219
	s_addc_u32 s1, vcc_hi, s6
	v_lshl_add_u64 v[178:179], s[0:1], 0, v[6:7]
	v_add_u32_e32 v6, s33, v220
	v_mov_b32_e32 v76, 0
	s_mov_b64 s[46:47], s[62:63]
	s_mov_b64 s[48:49], s[64:65]
	s_mov_b64 s[54:55], s[4:5]
	v_readlane_b32 s4, v254, 55
	v_readlane_b32 s62, v254, 57
	v_readlane_b32 s64, v254, 59
	v_mov_b32_e32 v161, v4
	s_mov_b32 s85, 0
	v_mov_b32_e32 v165, v4
	v_mov_b32_e32 v167, v4
	v_mov_b32_e32 v169, v4
	s_mov_b32 s7, 0x10000
	v_lshl_add_u64 v[180:181], s[0:1], 0, v[6:7]
	s_mov_b64 s[82:83], 0
	v_mov_b32_e32 v244, v221
	v_mov_b32_e32 v245, v197
	v_mov_b32_e32 v246, v216
	v_mov_b32_e32 v77, v76
	v_mov_b32_e32 v78, v76
	v_mov_b32_e32 v79, v76
	v_mov_b32_e32 v96, v76
	v_mov_b32_e32 v97, v76
	v_mov_b32_e32 v98, v76
	v_mov_b32_e32 v99, v76
	v_mov_b32_e32 v92, v76
	v_mov_b32_e32 v93, v76
	v_mov_b32_e32 v94, v76
	v_mov_b32_e32 v95, v76
	v_mov_b32_e32 v88, v76
	v_mov_b32_e32 v89, v76
	v_mov_b32_e32 v90, v76
	v_mov_b32_e32 v91, v76
	v_mov_b32_e32 v84, v76
	v_mov_b32_e32 v85, v76
	v_mov_b32_e32 v86, v76
	v_mov_b32_e32 v87, v76
	v_mov_b32_e32 v80, v76
	v_mov_b32_e32 v81, v76
	v_mov_b32_e32 v82, v76
	v_mov_b32_e32 v83, v76
	v_readlane_b32 s5, v254, 56
	v_readlane_b32 s63, v254, 58
	v_readlane_b32 s65, v254, 60
	s_waitcnt lgkmcnt(0)
	s_barrier
	v_readlane_b32 s44, v254, 8
	v_readlane_b32 s45, v254, 9
	v_readlane_b32 s50, v254, 14
	v_readlane_b32 s51, v254, 15
	v_readlane_b32 s42, v254, 45
	v_readlane_b32 s43, v254, 46
	s_branch .LBB0_250

; #define LAS __attribute__((address_space(3)))
; __device__ __forceinline__ void p2_mlstm(const Params& p, LAS unsigned char* lds) {
;     ...
;         for (int chunk = 0; chunk < 16; ++chunk) {
;             const int tok0 = tokbase + chunk * 128;
;             bf16x8 qf[8];
;             {
; #pragma unroll
;                 for (int kk = 0; kk < 8; ++kk) qf[kk] = __builtin_bit_cast(bf16x8, qfn[kk]);
; #pragma unroll
;                 for (int i = 0; i < 8; ++i) { const int vec = tid + 512 * i; *(LAS u32x4*)(KB + (vec >> 5) * KB_STRIDE + (vec & 31) * 16) = kreg[i]; }
;                 const int s = tid >> 2, vq = tid & 3;
;                 const float wgt = __expf(PU[chunk * 128 + s] - MM127[chunk]);
;                 float vf[8]; unpack8(vreg, vf);
; #pragma unroll
;                 for (int e = 0; e < 8; ++e) vf[e] *= wgt;
;                 *(LAS u32x4*)(VT + s * VR_STRIDE + vq * 16) = vreg;
;                 *(LAS u32x4*)(WVT + s * VR_STRIDE + vq * 16) = pack8(vf);
;                 if (vq == 0) *(LAS bf16_t*)(WV + s * 2) = f2bf(wgt);
;             }
;             __syncthreads();
;             u32x2 owr[2], zwr[2];
;             {
;                 const bf16_t* r1c = R1 + (size_t)tok0 * 5120;
; #pragma unroll
;                 for (int vt = 0; vt < 2; ++vt) { owr[vt] = ldg8(r1c, ooff + 32u * vt); zwr[vt] = ldg8(r1c, ooff + 2048u + 32u * vt); }
;             }
;             const int gl0 = chunk * 128;
;             const float mprev = MPREV[chunk], mm127 = MM127[chunk];
;             {
;                 const int l = 16 * wid + r;
;                 const float mml = fmaxf(mprev, PCM[gl0 + l]);
;                 f32x4 hacc[3];
;                 for (int mrep = 0; mrep < MLX2; ++mrep) {
; #pragma unroll
;                 for (int vt = 0; vt < 3; ++vt) hacc[vt] = (f32x4){0.f, 0.f, 0.f, 0.f};
; #pragma unroll
;                 for (int kh = 0; kh < 4; ++kh) {
;                     bf16x8 af[2][3];
; #pragma unroll
;                     for (int k4 = 0; k4 < 2; ++k4)
;                     {
; #pragma unroll
;                         for (int vt = 0; vt < 2; ++vt) {
;                             const u32x2 lo = tr_read(CT + (32 * (2 * kh + k4) + 8 * q + (r >> 2)) * VR_STRIDE + (16 * vt + 4 * (r & 3)) * 2);
;                             const u32x2 hi = tr_read(CT + (32 * (2 * kh + k4) + 8 * q + 4 + (r >> 2)) * VR_STRIDE + (16 * vt + 4 * (r & 3)) * 2);
.LBB0_250:
	s_add_i32 s35, s85, 0
	s_add_i32 s34, s35, 0x248c0
	ds_write_b128 v222, v[40:43]
	ds_write_b128 v223, v[44:47]
	ds_write_b128 v222, v[48:51] offset:16896
	ds_write_b128 v224, v[52:55]
	ds_write_b128 v222, v[56:59] offset:33792
	ds_write_b128 v225, v[60:63]
	ds_write_b128 v222, v[68:71] offset:50688
	ds_write_b128 v226, v[64:67]
	v_add_u32_e32 v5, 0, v244
	v_mov_b32_e32 v6, s34
	ds_read_b32 v5, v5
	ds_read_b32 v6, v6
	v_lshlrev_b32_e32 v100, 16, v72
	v_and_b32_e32 v101, 0xffff0000, v72
	v_lshlrev_b32_e32 v102, 16, v73
	v_and_b32_e32 v103, 0xffff0000, v73
	s_waitcnt lgkmcnt(0)
	v_sub_f32_e32 v5, v5, v6
	v_mul_f32_e32 v5, 0x3fb8aa3b, v5
	v_exp_f32_e32 v6, v5
	v_lshlrev_b32_e32 v104, 16, v74
	v_and_b32_e32 v105, 0xffff0000, v74
	v_lshlrev_b32_e32 v106, 16, v75
	v_and_b32_e32 v107, 0xffff0000, v75
	v_pk_mul_f32 v[100:101], v[6:7], v[100:101] op_sel_hi:[0,1]
	v_pk_mul_f32 v[102:103], v[6:7], v[102:103] op_sel_hi:[0,1]
	v_pk_mul_f32 v[104:105], v[6:7], v[104:105] op_sel_hi:[0,1]
	v_pk_mul_f32 v[106:107], v[6:7], v[106:107] op_sel_hi:[0,1]
	v_cvt_pk_bf16_f32 v100, v100, v101
	v_cvt_pk_bf16_f32 v101, v102, v103
	v_cvt_pk_bf16_f32 v102, v104, v105
	v_cvt_pk_bf16_f32 v103, v106, v107
	ds_write_b128 v227, v[72:75]
	ds_write_b128 v228, v[100:103]
	s_and_saveexec_b64 s[0:1], s[8:9]
	v_cvt_pk_bf16_f32 v5, v6, s0
	ds_write_b16 v229, v5
	s_or_b64 exec, exec, s[0:1]
	v_lshl_add_u64 v[6:7], v[176:177], 0, s[82:83]
	v_add_co_u32_e32 v6, vcc, 0x1d80000, v6
	s_waitcnt lgkmcnt(0)
	s_nop 0
	v_addc_co_u32_e32 v7, vcc, 0, v7, vcc
	s_barrier
	s_waitcnt vmcnt(2)
	v_lshl_add_u64 v[100:101], v[178:179], 0, s[82:83]
	v_lshl_add_u64 v[102:103], v[180:181], 0, s[82:83]
	global_load_dwordx2 v[188:189], v[6:7], off
	global_load_dwordx2 v[186:187], v[100:101], off
	global_load_dwordx2 v[182:183], v[102:103], off
	global_load_dwordx2 v[184:185], v[6:7], off offset:32
	s_cmp_eq_u32 s82, 0x12c0000
	s_cbranch_scc1 .Lml_nokv
	s_ashr_i32 s81, s80, 31
	s_lshl_b64 s[98:99], s[80:81], 12
	s_add_u32 s98, s94, s98
	s_addc_u32 s99, s95, s99
	s_add_u32 s100, s98, 0x10000
	s_addc_u32 s101, s99, 0
	global_load_dwordx4 v[40:43], v162, s[98:99] offset:2048
	global_load_dwordx4 v[44:47], v162, s[100:101] offset:2048
	global_load_dwordx4 v[48:51], v164, s[98:99]
	global_load_dwordx4 v[52:55], v164, s[100:101]
	global_load_dwordx4 v[56:59], v166, s[98:99]
	global_load_dwordx4 v[60:63], v166, s[100:101]
	global_load_dwordx4 v[68:71], v168, s[98:99]
	global_load_dwordx4 v[64:67], v168, s[100:101]
	v_mad_i64_i32 v[72:73], s[0:1], s80, v243, v[170:171]
	global_load_dwordx4 v[72:75], v[72:73], off
.Lml_nokv:
	s_add_i32 s0, s35, 0x24880
	v_mov_b32_e32 v5, s0
	v_add_u32_e32 v250, 0, v246
	v_mov_b32_e32 v6, s34
	v_add_u32_e32 v7, 0x20800, v250
	ds_read_b32 v247, v5
	ds_read_b32 v248, v6
	ds_read_b32 v5, v7
	ds_read_b64_tr_b16 v[104:105], v241
	ds_read_b64_tr_b16 v[100:101], v241 offset:32
	ds_read_b64_tr_b16 v[106:107], v241 offset:448
	ds_read_b64_tr_b16 v[102:103], v241 offset:480
	v_mov_b32_e32 v108, 0
	v_add_u32_e32 v249, 0, v197
	v_mov_b32_e32 v112, 0
	v_mov_b32_e32 v113, 0
	v_mov_b32_e32 v114, 0
	v_mov_b32_e32 v115, 0
	s_and_saveexec_b64 s[0:1], s[10:11]
	v_add_u32_e32 v6, 0x24900, v249
	ds_read_b128 v[112:115], v6
	s_or_b64 exec, exec, s[0:1]
	ds_read_b64_tr_b16 v[120:121], v241 offset:3584
	ds_read_b64_tr_b16 v[116:117], v241 offset:3616
	ds_read_b64_tr_b16 v[122:123], v241 offset:4032
	ds_read_b64_tr_b16 v[118:119], v241 offset:4064
	v_mov_b32_e32 v109, 0
	v_mov_b32_e32 v110, 0
	v_mov_b32_e32 v111, 0
	s_and_saveexec_b64 s[0:1], s[10:11]
	v_add_u32_e32 v6, 0x24940, v249
	ds_read_b128 v[108:111], v6
	s_or_b64 exec, exec, s[0:1]
	s_waitcnt lgkmcnt(5)
	v_mfma_f32_16x16x32_bf16 v[104:107], v[104:107], v[28:31], 0
	s_waitcnt lgkmcnt(4)
	v_mfma_f32_16x16x32_bf16 v[124:127], v[100:103], v[28:31], 0
	v_mfma_f32_16x16x32_bf16 v[112:115], v[112:115], v[28:31], 0
	s_waitcnt lgkmcnt(1)
	v_mfma_f32_16x16x32_bf16 v[100:103], v[120:123], v[8:11], v[104:107]
	s_waitcnt lgkmcnt(0)
	v_mfma_f32_16x16x32_bf16 v[104:107], v[116:119], v[8:11], v[124:127]
	v_mfma_f32_16x16x32_bf16 v[108:111], v[108:111], v[8:11], v[112:115]
	ds_read_b64_tr_b16 v[116:117], v230
	s_nop 1
	ds_read_b64_tr_b16 v[112:113], v230 offset:32
	ds_read_b64_tr_b16 v[118:119], v230 offset:448
	ds_read_b64_tr_b16 v[114:115], v230 offset:480
	v_mov_b32_e32 v120, 0
	v_mov_b32_e32 v124, 0
	v_mov_b32_e32 v125, 0
	v_mov_b32_e32 v126, 0
	v_mov_b32_e32 v127, 0
	s_and_saveexec_b64 s[0:1], s[10:11]
	v_add_u32_e32 v6, 0x24980, v249
	ds_read_b128 v[124:127], v6
	s_or_b64 exec, exec, s[0:1]
	ds_read_b64_tr_b16 v[132:133], v241 offset:10752
	ds_read_b64_tr_b16 v[128:129], v241 offset:10784
	ds_read_b64_tr_b16 v[134:135], v241 offset:11200
	ds_read_b64_tr_b16 v[130:131], v241 offset:11232
	v_mov_b32_e32 v121, 0
	v_mov_b32_e32 v122, 0
	v_mov_b32_e32 v123, 0
	s_and_saveexec_b64 s[0:1], s[10:11]
	v_add_u32_e32 v6, 0x249c0, v249
	ds_read_b128 v[120:123], v6
	s_or_b64 exec, exec, s[0:1]
	s_waitcnt lgkmcnt(5)
	v_mfma_f32_16x16x32_bf16 v[100:103], v[116:119], v[12:15], v[100:103]
	s_waitcnt lgkmcnt(4)
; __device__ __forceinline__ void p2_mlstm(const Params& p, LAS unsigned char* lds) {
;     ...
;                 for (int kh = 0; kh < 4; ++kh) {
;                     bf16x8 af[2][3];
; #pragma unroll
;                     for (int k4 = 0; k4 < 2; ++k4)
;                     {
; #pragma unroll
;                         for (int vt = 0; vt < 2; ++vt) {
;                             const u32x2 lo = tr_read(CT + (32 * (2 * kh + k4) + 8 * q + (r >> 2)) * VR_STRIDE + (16 * vt + 4 * (r & 3)) * 2);
;                             const u32x2 hi = tr_read(CT + (32 * (2 * kh + k4) + 8 * q + 4 + (r >> 2)) * VR_STRIDE + (16 * vt + 4 * (r & 3)) * 2);
;                             u32x4 cw; cw.x = lo.x; cw.y = lo.y; cw.z = hi.x; cw.w = hi.y; af[k4][vt] = __builtin_bit_cast(bf16x8, cw);
;                         }
;                         u32x4 nz = (u32x4){0u, 0u, 0u, 0u};
;                         if (r == 0) nz = *(const LAS u32x4*)(NV + (32 * (2 * kh + k4) + 8 * q) * 2);
;                         af[k4][2] = __builtin_bit_cast(bf16x8, nz);
;                     }
;                     __builtin_amdgcn_sched_barrier(0);
; #pragma unroll
;                     for (int k4 = 0; k4 < 2; ++k4)
; #pragma unroll
;                         for (int vt = 0; vt < 3; ++vt) hacc[vt] = __builtin_amdgcn_mfma_f32_16x16x32_bf16(af[k4][vt], qf[2 * kh + k4], hacc[vt], 0, 0, 0);
;                     __builtin_amdgcn_sched_barrier(0);
;                 }
;                 const float inter = __expf(mprev - mml);
; #pragma unroll
;                 for (int vt = 0; vt < 3; ++vt) hacc[vt] *= inter;
;                 {
;                     const int nb = 4 * ((wid >> 1) + 1);
;                     bf16x8 fa0[2], fa1[2], fb0[2], fb1[2];
;     ...
;                     ML_LDB(fa0, fa1, 0);
;                     f32x4 s0 = (f32x4){0.f, 0.f, 0.f, 0.f}, s1 = s0;
; #pragma unroll
;                     for (int bb = 0; bb < 16; ++bb) {
;                         if (bb < nb) {
;                             if (bb + 1 < nb) { if (bb & 1) ML_LDB(fa0, fa1, bb + 1); else ML_LDB(fb0, fb1, bb + 1); }
;                             __builtin_amdgcn_sched_barrier(0);
; #pragma unroll
;                             for (int k4 = 0; k4 < 2; ++k4) {
;                                 s0 = __builtin_amdgcn_mfma_f32_16x16x32_bf16((bb & 1) ? fb0[k4] : fa0[k4], qf[2 * (bb & 3) + k4], s0, 0, 0, 0);
	v_mfma_f32_16x16x32_bf16 v[104:107], v[112:115], v[12:15], v[104:107]
	v_mfma_f32_16x16x32_bf16 v[108:111], v[124:127], v[12:15], v[108:111]
	s_waitcnt lgkmcnt(1)
	v_mfma_f32_16x16x32_bf16 v[100:103], v[132:135], v[16:19], v[100:103]
	s_waitcnt lgkmcnt(0)
	v_mfma_f32_16x16x32_bf16 v[104:107], v[128:131], v[16:19], v[104:107]
	v_mfma_f32_16x16x32_bf16 v[108:111], v[120:123], v[16:19], v[108:111]
	ds_read_b64_tr_b16 v[116:117], v241 offset:14336
	ds_read_b64_tr_b16 v[112:113], v241 offset:14368
	ds_read_b64_tr_b16 v[118:119], v241 offset:14784
	ds_read_b64_tr_b16 v[114:115], v241 offset:14816
	v_mov_b32_e32 v120, 0
	v_mov_b32_e32 v124, 0
	v_mov_b32_e32 v125, 0
	v_mov_b32_e32 v126, 0
	v_mov_b32_e32 v127, 0
	s_and_saveexec_b64 s[0:1], s[10:11]
	v_add_u32_e32 v6, 0x24a00, v249
	ds_read_b128 v[124:127], v6
	s_or_b64 exec, exec, s[0:1]
	ds_read_b64_tr_b16 v[132:133], v241 offset:17920
	ds_read_b64_tr_b16 v[128:129], v241 offset:17952
	ds_read_b64_tr_b16 v[134:135], v241 offset:18368
	ds_read_b64_tr_b16 v[130:131], v241 offset:18400
	v_mov_b32_e32 v121, 0
	v_mov_b32_e32 v122, 0
	v_mov_b32_e32 v123, 0
	s_and_saveexec_b64 s[0:1], s[10:11]
	v_add_u32_e32 v6, 0x24a40, v249
	ds_read_b128 v[120:123], v6
	s_or_b64 exec, exec, s[0:1]
	s_waitcnt lgkmcnt(5)
	v_mfma_f32_16x16x32_bf16 v[100:103], v[116:119], v[20:23], v[100:103]
	s_waitcnt lgkmcnt(4)
	v_mfma_f32_16x16x32_bf16 v[104:107], v[112:115], v[20:23], v[104:107]
	v_mfma_f32_16x16x32_bf16 v[108:111], v[124:127], v[20:23], v[108:111]
	s_waitcnt lgkmcnt(1)
	v_mfma_f32_16x16x32_bf16 v[100:103], v[132:135], v[24:27], v[100:103]
	s_waitcnt lgkmcnt(0)
	v_mfma_f32_16x16x32_bf16 v[104:107], v[128:131], v[24:27], v[104:107]
	v_mfma_f32_16x16x32_bf16 v[108:111], v[120:123], v[24:27], v[108:111]
	ds_read_b64_tr_b16 v[116:117], v241 offset:21504
	ds_read_b64_tr_b16 v[112:113], v241 offset:21536
	ds_read_b64_tr_b16 v[118:119], v241 offset:21952
	ds_read_b64_tr_b16 v[114:115], v241 offset:21984
	v_mov_b32_e32 v120, 0
	v_mov_b32_e32 v124, 0
	v_mov_b32_e32 v125, 0
	v_mov_b32_e32 v126, 0
	v_mov_b32_e32 v127, 0
	s_and_saveexec_b64 s[0:1], s[10:11]
	v_add_u32_e32 v6, 0x24a80, v249
	ds_read_b128 v[124:127], v6
	s_or_b64 exec, exec, s[0:1]
	ds_read_b64_tr_b16 v[132:133], v241 offset:25088
	ds_read_b64_tr_b16 v[128:129], v241 offset:25120
	ds_read_b64_tr_b16 v[134:135], v241 offset:25536
	ds_read_b64_tr_b16 v[130:131], v241 offset:25568
	v_mov_b32_e32 v121, 0
	v_mov_b32_e32 v122, 0
	v_mov_b32_e32 v123, 0
	s_and_saveexec_b64 s[0:1], s[10:11]
	v_add_u32_e32 v6, 0x24ac0, v249
	ds_read_b128 v[120:123], v6
	s_or_b64 exec, exec, s[0:1]
	s_waitcnt lgkmcnt(5)
	v_mfma_f32_16x16x32_bf16 v[100:103], v[116:119], v[32:35], v[100:103]
	s_waitcnt lgkmcnt(4)
	v_mfma_f32_16x16x32_bf16 v[104:107], v[112:115], v[32:35], v[104:107]
	v_mfma_f32_16x16x32_bf16 v[108:111], v[124:127], v[32:35], v[108:111]
	s_waitcnt lgkmcnt(1)
	v_mfma_f32_16x16x32_bf16 v[140:143], v[132:135], v[36:39], v[100:103]
	s_waitcnt lgkmcnt(0)
	v_mfma_f32_16x16x32_bf16 v[104:107], v[128:131], v[36:39], v[104:107]
	v_mfma_f32_16x16x32_bf16 v[100:103], v[120:123], v[36:39], v[108:111]
	s_nop 2
	ds_read_b128 v[108:111], v198
	ds_read_b128 v[112:115], v198 offset:64
	ds_read_b128 v[116:119], v198 offset:8448
	ds_read_b128 v[120:123], v198 offset:8512
	ds_read_b128 v[124:127], v198 offset:128
	ds_read_b128 v[144:147], v198 offset:192
	ds_read_b128 v[148:151], v198 offset:8576
	ds_read_b128 v[152:155], v198 offset:8640
	s_waitcnt lgkmcnt(7)
	v_mfma_f32_16x16x32_bf16 v[108:111], v[108:111], v[28:31], 0
	s_waitcnt lgkmcnt(5)
	v_mfma_f32_16x16x32_bf16 v[116:119], v[116:119], v[28:31], 0
	v_mfma_f32_16x16x32_bf16 v[108:111], v[112:115], v[8:11], v[108:111]
	s_waitcnt lgkmcnt(4)
	v_mfma_f32_16x16x32_bf16 v[112:115], v[120:123], v[8:11], v[116:119]
	s_nop 4
	ds_read_b128 v[116:119], v198 offset:256
	ds_read_b128 v[128:131], v198 offset:320
	ds_read_b128 v[132:135], v198 offset:8704
	ds_read_b128 v[136:139], v198 offset:8768
	s_waitcnt lgkmcnt(7)
	v_mfma_f32_16x16x32_bf16 v[108:111], v[124:127], v[12:15], v[108:111]
	s_waitcnt lgkmcnt(5)
	v_mfma_f32_16x16x32_bf16 v[112:115], v[148:151], v[12:15], v[112:115]
	v_mfma_f32_16x16x32_bf16 v[144:147], v[144:147], v[16:19], v[108:111]
	s_waitcnt lgkmcnt(4)
	v_mfma_f32_16x16x32_bf16 v[148:151], v[152:155], v[16:19], v[112:115]
	s_nop 2
	ds_read_b128 v[108:111], v198 offset:384
	s_nop 0
	ds_read_b128 v[112:115], v198 offset:448
	ds_read_b128 v[120:123], v198 offset:8832
	ds_read_b128 v[124:127], v198 offset:8896
	s_waitcnt lgkmcnt(7)
	v_mfma_f32_16x16x32_bf16 v[144:147], v[116:119], v[20:23], v[144:147]
	s_waitcnt lgkmcnt(5)
	v_mfma_f32_16x16x32_bf16 v[148:151], v[132:135], v[20:23], v[148:151]
	v_mfma_f32_16x16x32_bf16 v[144:147], v[128:131], v[24:27], v[144:147]
	s_waitcnt lgkmcnt(4)
	v_mfma_f32_16x16x32_bf16 v[148:151], v[136:139], v[24:27], v[148:151]
	v_cndmask_b32_e64 v6, 0, 1, s[38:39]
	v_cmp_ne_u32_e64 s[34:35], 1, v6
	s_andn2_b64 vcc, exec, s[38:39]
	s_cbranch_vccnz .LBB0_270
	ds_read_b128 v[116:119], v198 offset:16896
	ds_read_b128 v[128:131], v198 offset:16960
	ds_read_b128 v[132:135], v198 offset:25344
	ds_read_b128 v[136:139], v198 offset:25408

; __device__ __forceinline__ float bflo(unsigned w) { return __uint_as_float(w << 16); }
; __device__ __forceinline__ float bfhi(unsigned w) { return __uint_as_float(w & 0xffff0000u); }
; __device__ __forceinline__ unsigned cvt_pk_bf16(float lo, float hi) { const f32x2_t f = {lo, hi}; const bf16x2_t b = __builtin_convertvector(f, bf16x2_t); return __builtin_bit_cast(unsigned, b); }
; __device__ __forceinline__ float sigmoidf_(float x) { return __builtin_amdgcn_rcpf(1.0f + __expf(-x)); }
; __device__ __forceinline__ float siluf_(float x) { return x * sigmoidf_(x); }
; __device__ __forceinline__ void p2_mlstm(const Params& p, LAS unsigned char* lds) {
;     ...
;                 const float den = __shfl(hacc[2][0], r);
;                 const float dn = fmaxf(fabsf(den), __expf(-(PB[gl0 + l] + mml)));
;                 const float rdn = 1.0f / dn;
;                 const int t = tok0 + l;
;                 float ssq = 0.f;
; #pragma unroll
;                 for (int vt = 0; vt < 2; ++vt) {
;                     const int c = h * 256 + sl * 32 + 16 * vt + 4 * q;
;                     const u32x2 ow = owr[vt], zw = zwr[vt];
;                     const float4 nw = *(const float4*)(p.m_norm_w + c);
;                     const float og[4] = {bflo(ow.x), bfhi(ow.x), bflo(ow.y), bfhi(ow.y)};
;                     const float zg[4] = {bflo(zw.x), bfhi(zw.x), bflo(zw.y), bfhi(zw.y)};
;                     const float nwv[4] = {nw.x, nw.y, nw.z, nw.w};
;                     float uo[4];
; #pragma unroll
;                     for (int j = 0; j < 4; ++j) { const float hs = hacc[vt][j] * rdn * sigmoidf_(og[j]); ssq += hs * hs; uo[j] = hs * nwv[j] * siluf_(zg[j]); }
;                     u32x2 w; w.x = cvt_pk_bf16(uo[0], uo[1]); w.y = cvt_pk_bf16(uo[2], uo[3]);
;                     stg8(HM + (size_t)tok0 * 1024, hoff + 32u * vt, w);
;                 }
;                 ssq += __shfl_xor(ssq, 16); ssq += __shfl_xor(ssq, 32);
;                 if (q == 0) SSQ[((size_t)t * 4 + h) * 8 + sl] = ssq;
;                 if (chunk < 15) {
;                     const bf16_t* qkc = QK + (size_t)(tok0 + 128) * 2048; const bf16_t* r1c = R1 + (size_t)(tok0 + 128) * 5120;
; #pragma unroll
;                     for (int kk = 0; kk < 8; ++kk) qfn[kk] = ldg16(qkc, qoff + 64u * kk);
.LBB0_343:
	v_lshlrev_b32_e32 v128, 2, v195
	v_add_u32_e32 v128, 0x24c00, v128
	ds_read_b128 v[120:123], v128
	ds_read_b128 v[124:127], v128 offset:64
	v_add_u32_e32 v6, 0x22800, v250
	ds_read_b32 v6, v6
	s_nop 5
	ds_bpermute_b32 v5, v204, v140
	s_waitcnt vmcnt(0) lgkmcnt(4)
	s_cmp_eq_u32 s82, 0x12c0000
	s_cbranch_scc1 .Lml_noq
	s_ashr_i32 s81, s80, 31
	s_lshl_b64 s[98:99], s[80:81], 12
	s_add_u32 s98, s94, s98
	s_addc_u32 s99, s95, s99
	global_load_dwordx4 v[28:31], v160, s[98:99]
	global_load_dwordx4 v[8:11], v160, s[98:99] offset:64
	global_load_dwordx4 v[12:15], v160, s[98:99] offset:128
	global_load_dwordx4 v[16:19], v160, s[98:99] offset:192
	global_load_dwordx4 v[20:23], v160, s[98:99] offset:256
	global_load_dwordx4 v[24:27], v160, s[98:99] offset:320
	global_load_dwordx4 v[32:35], v160, s[98:99] offset:384
	global_load_dwordx4 v[36:39], v160, s[98:99] offset:448
.Lml_noq:
	v_lshlrev_b32_e32 v114, 16, v186
	v_and_b32_e32 v115, 0xffff0000, v186
	v_lshlrev_b32_e32 v118, 16, v189
	s_waitcnt lgkmcnt(1)
	v_add_f32_e32 v6, v251, v6
	v_mul_f32_e32 v6, 0xbfb8aa3b, v6
	v_exp_f32_e32 v6, v6
	s_waitcnt lgkmcnt(0)
	v_max_f32_e64 v5, |v5|, |v5|
	v_and_b32_e32 v119, 0xffff0000, v189
	v_max_f32_e32 v5, v5, v6
	v_div_scale_f32 v6, s[0:1], v5, v5, 1.0
	v_rcp_f32_e32 v7, v6
	s_nop 0
	v_fma_f32 v108, -v6, v7, 1.0
	v_fmac_f32_e32 v7, v108, v7
	v_div_scale_f32 v108, vcc, 1.0, v5, 1.0
	v_mul_f32_e32 v109, v108, v7
	v_fma_f32 v110, -v6, v109, v108
	v_fmac_f32_e32 v109, v110, v7
	v_fma_f32 v6, -v6, v109, v108
	v_div_fmas_f32 v6, v6, v7, v109
	v_div_fixup_f32 v6, v6, v5, 1.0
	v_lshlrev_b32_e32 v5, 16, v188
	v_mul_f32_e32 v5, 0xbfb8aa3b, v5
	v_exp_f32_e32 v5, v5
	v_and_b32_e32 v7, 0xffff0000, v188
	v_pk_mul_f32 v[104:105], v[104:105], v[6:7] op_sel_hi:[1,0]
	v_pk_mul_f32 v[106:107], v[106:107], v[6:7] op_sel_hi:[1,0]
	v_add_f32_e32 v5, 1.0, v5
	v_rcp_f32_e32 v112, v5
	v_mul_f32_e32 v5, 0xbfb8aa3b, v7
	v_exp_f32_e32 v5, v5
	v_and_b32_e32 v7, 0xffff0000, v184
	v_pk_mul_f32 v[100:101], v[100:101], v[6:7] op_sel_hi:[1,0]
	v_add_f32_e32 v5, 1.0, v5
	v_rcp_f32_e32 v113, v5
	v_mul_f32_e32 v5, 0xbfb8aa3b, v114
	v_exp_f32_e32 v5, v5
	v_pk_mul_f32 v[112:113], v[112:113], v[104:105]
	s_nop 0
	v_pk_mul_f32 v[104:105], v[112:113], v[112:113]
	v_add_f32_e32 v5, 1.0, v5
	v_rcp_f32_e32 v116, v5
	v_mul_f32_e32 v5, 0xbfb8aa3b, v115
	v_exp_f32_e32 v5, v5
	v_pk_mul_f32 v[108:109], v[120:121], v[112:113]
	v_add_f32_e32 v5, 1.0, v5
	v_rcp_f32_e32 v117, v5
	v_mul_f32_e32 v5, 0xbfb8aa3b, v118
	v_exp_f32_e32 v5, v5
	v_lshlrev_b32_e32 v118, 16, v185
	v_pk_mul_f32 v[112:113], v[116:117], v[114:115]
	v_lshlrev_b32_e32 v114, 16, v187
	v_add_f32_e32 v5, 1.0, v5
	v_pk_mul_f32 v[108:109], v[112:113], v[108:109]
	v_rcp_f32_e32 v112, v5
	v_mul_f32_e32 v5, 0xbfb8aa3b, v119
	v_exp_f32_e32 v5, v5
	v_and_b32_e32 v115, 0xffff0000, v187
	v_cvt_pk_bf16_f32 v108, v108, v109
	v_and_b32_e32 v119, 0xffff0000, v185
	v_add_f32_e32 v5, 1.0, v5
	v_rcp_f32_e32 v113, v5
	v_mul_f32_e32 v5, 0xbfb8aa3b, v114
	v_exp_f32_e32 v5, v5
	v_pk_mul_f32 v[112:113], v[112:113], v[106:107]
	s_nop 0
	v_pk_mul_f32 v[106:107], v[112:113], v[112:113]
	v_add_f32_e32 v5, 1.0, v5
	v_rcp_f32_e32 v116, v5
	v_mul_f32_e32 v5, 0xbfb8aa3b, v115
	v_exp_f32_e32 v5, v5
	v_pk_mul_f32 v[110:111], v[122:123], v[112:113]
	v_add_f32_e32 v5, 1.0, v5
	v_rcp_f32_e32 v117, v5
	v_lshlrev_b32_e32 v5, 16, v184
	v_mul_f32_e32 v5, 0xbfb8aa3b, v5
	v_exp_f32_e32 v5, v5
	v_pk_mul_f32 v[112:113], v[116:117], v[114:115]
	v_lshlrev_b32_e32 v114, 16, v182
	v_pk_mul_f32 v[110:111], v[112:113], v[110:111]
	v_add_f32_e32 v5, 1.0, v5
	v_cvt_pk_bf16_f32 v109, v110, v111
	global_store_dwordx2 v[174:175], v[108:109], off
	v_rcp_f32_e32 v112, v5
	v_mul_f32_e32 v5, 0xbfb8aa3b, v7
	v_exp_f32_e32 v5, v5
	v_and_b32_e32 v115, 0xffff0000, v182
	v_pk_mul_f32 v[6:7], v[102:103], v[6:7] op_sel_hi:[1,0]
	v_add_f32_e32 v5, 1.0, v5
	v_rcp_f32_e32 v113, v5
	v_mul_f32_e32 v5, 0xbfb8aa3b, v114
	v_exp_f32_e32 v5, v5
	v_pk_mul_f32 v[100:101], v[112:113], v[100:101]
	s_nop 0
	v_pk_mul_f32 v[112:113], v[100:101], v[100:101]
	v_add_f32_e32 v5, 1.0, v5
	v_rcp_f32_e32 v116, v5
	v_mul_f32_e32 v5, 0xbfb8aa3b, v115
	v_exp_f32_e32 v5, v5
	v_pk_mul_f32 v[100:101], v[124:125], v[100:101]
	v_add_f32_e32 v5, 1.0, v5
	v_rcp_f32_e32 v117, v5
	v_mul_f32_e32 v5, 0xbfb8aa3b, v118
	v_exp_f32_e32 v5, v5
	v_pk_mul_f32 v[108:109], v[116:117], v[114:115]
	s_nop 0
	v_pk_mul_f32 v[100:101], v[108:109], v[100:101]
	v_add_f32_e32 v5, 1.0, v5
	v_rcp_f32_e32 v108, v5
	v_mul_f32_e32 v5, 0xbfb8aa3b, v119
	v_exp_f32_e32 v5, v5
	v_lshlrev_b32_e32 v114, 16, v183
	v_and_b32_e32 v115, 0xffff0000, v183
	v_cvt_pk_bf16_f32 v100, v100, v101
	v_add_f32_e32 v5, 1.0, v5
	v_rcp_f32_e32 v109, v5
	v_mul_f32_e32 v5, 0xbfb8aa3b, v114
	v_exp_f32_e32 v5, v5
	v_pk_mul_f32 v[6:7], v[108:109], v[6:7]
	s_nop 0
	v_pk_mul_f32 v[102:103], v[6:7], v[6:7]
	v_add_f32_e32 v5, 1.0, v5
	v_rcp_f32_e32 v108, v5
	v_add_f32_e32 v5, v104, v105
	v_add_f32_e32 v5, v106, v5
	v_add_f32_e32 v5, v107, v5
	v_add_f32_e32 v5, v112, v5
	v_add_f32_e32 v5, v113, v5
	v_add_f32_e32 v5, v102, v5
	v_mul_f32_e32 v102, 0xbfb8aa3b, v115
	v_exp_f32_e32 v102, v102
	v_add_f32_e32 v5, v103, v5
	v_pk_mul_f32 v[6:7], v[6:7], v[126:127]
	v_add_f32_e32 v102, 1.0, v102
	v_rcp_f32_e32 v109, v102
	s_nop 0
	v_pk_mul_f32 v[102:103], v[108:109], v[114:115]
	s_nop 0
	v_pk_mul_f32 v[6:7], v[102:103], v[6:7]
	s_nop 0
	v_cvt_pk_bf16_f32 v101, v6, v7
	ds_bpermute_b32 v6, v205, v5
	global_store_dwordx2 v[174:175], v[100:101], off offset:32
	s_waitcnt lgkmcnt(0)
	v_add_f32_e32 v5, v5, v6
	ds_bpermute_b32 v6, v206, v5
	s_and_saveexec_b64 s[0:1], s[12:13]
	s_cbranch_execz .LBB0_345
	s_waitcnt lgkmcnt(0)
	v_add_f32_e32 v5, v5, v6
	v_add_u32_e32 v6, s80, v202
	v_add_u32_e32 v6, 0xffffff80, v6
	v_ashrrev_i32_e32 v7, 31, v6
	v_lshlrev_b64 v[6:7], 7, v[6:7]
	v_lshl_add_u64 v[6:7], s[78:79], 0, v[6:7]
	global_store_dword v[6:7], v5, off
; __device__ __forceinline__ void p2_mlstm(const Params& p, LAS unsigned char* lds) {
;     ...
;                 if (chunk < 15) {
;                     const bf16_t* qkc = QK + (size_t)(tok0 + 128) * 2048; const bf16_t* r1c = R1 + (size_t)(tok0 + 128) * 5120;
; #pragma unroll
;                     for (int kk = 0; kk < 8; ++kk) qfn[kk] = ldg16(qkc, qoff + 64u * kk);
; #pragma unroll
;                     for (int i = 0; i < 8; ++i) kreg[i] = ldg16(qkc, koff + 65536u * i);
;                     vreg = ldg16(r1c, voff);
;                 }
;                 const float decay = __expf(mprev - mm127);
; #pragma unroll
;                 for (int vt = 0; vt < 3; ++vt)
; #pragma unroll
;                     for (int dd = 0; dd < 2; ++dd) cacc[vt][dd] *= decay;
; #pragma unroll
;                 for (int kk = 0; kk < 4; ++kk) {
;                     bf16x8 kb[2], wa[3];
; #pragma unroll
;                     for (int dd = 0; dd < 2; ++dd) {
;                         const u32x2 lo = tr_read(KB + (32 * kk + 8 * q + (r >> 2)) * KB_STRIDE + (16 * (2 * wid + dd) + 4 * (r & 3)) * 2);
;                         const u32x2 hi = tr_read(KB + (32 * kk + 8 * q + 4 + (r >> 2)) * KB_STRIDE + (16 * (2 * wid + dd) + 4 * (r & 3)) * 2);
;                         u32x4 kw; kw.x = lo.x; kw.y = lo.y; kw.z = hi.x; kw.w = hi.y; kb[dd] = __builtin_bit_cast(bf16x8, kw);
;                     }
; #pragma unroll
;                     for (int vt = 0; vt < 2; ++vt) {
;                         const u32x2 lo = tr_read(WVT + (32 * kk + 8 * q + (r >> 2)) * VR_STRIDE + (16 * vt + 4 * (r & 3)) * 2);
;                         const u32x2 hi = tr_read(WVT + (32 * kk + 8 * q + 4 + (r >> 2)) * VR_STRIDE + (16 * vt + 4 * (r & 3)) * 2);
;                         u32x4 ww; ww.x = lo.x; ww.y = lo.y; ww.z = hi.x; ww.w = hi.y; wa[vt] = __builtin_bit_cast(bf16x8, ww);
;                     }
;                     { u32x4 wz = (u32x4){0u, 0u, 0u, 0u}; if (r == 0) wz = *(const LAS u32x4*)(WV + (32 * kk + 8 * q) * 2); wa[2] = __builtin_bit_cast(bf16x8, wz); }
;                     __builtin_amdgcn_sched_barrier(0);
; #pragma unroll
;                     for (int vt = 0; vt < 3; ++vt)
; #pragma unroll
;                         for (int dd = 0; dd < 2; ++dd) cacc[vt][dd] = __builtin_amdgcn_mfma_f32_16x16x32_bf16(wa[vt], kb[dd], cacc[vt][dd], 0, 0, 0);
;                     __builtin_amdgcn_sched_barrier(0);
.LBB0_345:
	s_or_b64 exec, exec, s[0:1]
.LBB0_347:
	ds_read_b64_tr_b16 v[106:107], v231
	ds_read_b64_tr_b16 v[102:103], v231 offset:32
	ds_read_b64_tr_b16 v[108:109], v231 offset:2112
	ds_read_b64_tr_b16 v[104:105], v231 offset:2144
	ds_read_b64_tr_b16 v[114:115], v232
	ds_read_b64_tr_b16 v[110:111], v232 offset:32
	ds_read_b64_tr_b16 v[116:117], v232 offset:448
	ds_read_b64_tr_b16 v[112:113], v232 offset:480
	v_mov_b32_e32 v100, 0
	v_mov_b32_e32 v118, 0
	v_mov_b32_e32 v119, 0
	v_mov_b32_e32 v120, 0
	v_mov_b32_e32 v121, 0
	s_and_saveexec_b64 s[0:1], s[10:11]
	v_add_u32_e32 v5, 0x24b00, v249
	ds_read_b128 v[118:121], v5
	s_or_b64 exec, exec, s[0:1]
	v_sub_f32_e32 v5, v247, v248
	v_mul_f32_e32 v5, 0x3fb8aa3b, v5
	s_waitcnt lgkmcnt(8)
	v_exp_f32_e32 v6, v5
	s_nop 0
	v_pk_mul_f32 v[78:79], v[78:79], v[6:7] op_sel_hi:[1,0]
	v_pk_mul_f32 v[76:77], v[76:77], v[6:7] op_sel_hi:[1,0]
	v_pk_mul_f32 v[98:99], v[98:99], v[6:7] op_sel_hi:[1,0]
	v_pk_mul_f32 v[96:97], v[96:97], v[6:7] op_sel_hi:[1,0]
	v_pk_mul_f32 v[94:95], v[94:95], v[6:7] op_sel_hi:[1,0]
	v_pk_mul_f32 v[92:93], v[92:93], v[6:7] op_sel_hi:[1,0]
	v_pk_mul_f32 v[90:91], v[90:91], v[6:7] op_sel_hi:[1,0]
	v_pk_mul_f32 v[88:89], v[88:89], v[6:7] op_sel_hi:[1,0]
	v_pk_mul_f32 v[124:125], v[86:87], v[6:7] op_sel_hi:[1,0]
	v_pk_mul_f32 v[122:123], v[84:85], v[6:7] op_sel_hi:[1,0]
	v_pk_mul_f32 v[128:129], v[82:83], v[6:7] op_sel_hi:[1,0]
	v_pk_mul_f32 v[126:127], v[80:81], v[6:7] op_sel_hi:[1,0]
	s_waitcnt lgkmcnt(1)
	v_mfma_f32_16x16x32_bf16 v[76:79], v[114:117], v[106:109], v[76:79]
	v_mfma_f32_16x16x32_bf16 v[80:83], v[114:117], v[102:105], v[96:99]
	s_waitcnt lgkmcnt(0)
	v_mfma_f32_16x16x32_bf16 v[84:87], v[110:113], v[106:109], v[92:95]
	v_mfma_f32_16x16x32_bf16 v[88:91], v[110:113], v[102:105], v[88:91]
	v_mfma_f32_16x16x32_bf16 v[92:95], v[118:121], v[106:109], v[122:125]
	v_mfma_f32_16x16x32_bf16 v[96:99], v[118:121], v[102:105], v[126:129]
	v_add_u32_e32 v5, v199, v196
	ds_read_b64_tr_b16 v[112:113], v233
	ds_read_b64_tr_b16 v[108:109], v233 offset:32
	ds_read_b64_tr_b16 v[114:115], v233 offset:2112
	ds_read_b64_tr_b16 v[110:111], v233 offset:2144
	ds_read_b64_tr_b16 v[104:105], v5
	ds_read_b64_tr_b16 v[116:117], v5 offset:32
	ds_read_b64_tr_b16 v[106:107], v5 offset:448
	ds_read_b64_tr_b16 v[118:119], v5 offset:480
	v_mov_b32_e32 v101, 0
	v_mov_b32_e32 v102, 0
	v_mov_b32_e32 v103, 0
	s_and_saveexec_b64 s[0:1], s[10:11]
	s_add_i32 s6, 0, 0x24b00
	v_add_u32_e32 v5, s6, v197
	ds_read_b128 v[100:103], v5 offset:64
	s_or_b64 exec, exec, s[0:1]
	s_waitcnt lgkmcnt(1)
	v_mfma_f32_16x16x32_bf16 v[76:79], v[104:107], v[112:115], v[76:79]
	v_mfma_f32_16x16x32_bf16 v[104:107], v[104:107], v[108:111], v[80:83]
	s_waitcnt lgkmcnt(0)
	v_mfma_f32_16x16x32_bf16 v[82:85], v[116:119], v[112:115], v[84:87]
	v_mfma_f32_16x16x32_bf16 v[86:89], v[116:119], v[108:111], v[88:91]
	v_mfma_f32_16x16x32_bf16 v[90:93], v[100:103], v[112:115], v[92:95]
	v_mfma_f32_16x16x32_bf16 v[94:97], v[100:103], v[108:111], v[96:99]
	ds_read_b64_tr_b16 v[114:115], v234
	ds_read_b64_tr_b16 v[110:111], v234 offset:32
	ds_read_b64_tr_b16 v[116:117], v234 offset:2112
	ds_read_b64_tr_b16 v[112:113], v234 offset:2144
	ds_read_b64_tr_b16 v[98:99], v235
	ds_read_b64_tr_b16 v[118:119], v235 offset:32
	ds_read_b64_tr_b16 v[100:101], v235 offset:448
	ds_read_b64_tr_b16 v[120:121], v235 offset:480
	v_mov_b32_e32 v80, 0
	v_mov_b32_e32 v122, 0
	v_mov_b32_e32 v123, 0
	v_mov_b32_e32 v124, 0
	v_mov_b32_e32 v125, 0
	s_and_saveexec_b64 s[0:1], s[10:11]
	s_add_i32 s6, 0, 0x24b00
	v_add_u32_e32 v5, s6, v197
	ds_read_b128 v[122:125], v5 offset:128
	s_or_b64 exec, exec, s[0:1]
	s_waitcnt lgkmcnt(1)
	v_mfma_f32_16x16x32_bf16 v[76:79], v[98:101], v[114:117], v[76:79]
	v_mfma_f32_16x16x32_bf16 v[98:101], v[98:101], v[110:113], v[104:107]
	s_waitcnt lgkmcnt(0)
	v_mfma_f32_16x16x32_bf16 v[102:105], v[118:121], v[114:117], v[82:85]
	v_mfma_f32_16x16x32_bf16 v[84:87], v[118:121], v[110:113], v[86:89]
	v_mfma_f32_16x16x32_bf16 v[106:109], v[122:125], v[114:117], v[90:93]
	v_mfma_f32_16x16x32_bf16 v[110:113], v[122:125], v[110:113], v[94:97]
	v_add_u32_e32 v5, v200, v207
	ds_read_b64_tr_b16 v[118:119], v5
	ds_read_b64_tr_b16 v[114:115], v5 offset:32
	ds_read_b64_tr_b16 v[120:121], v5 offset:2112
	ds_read_b64_tr_b16 v[116:117], v5 offset:2144
	ds_read_b64_tr_b16 v[92:93], v236
	ds_read_b64_tr_b16 v[88:89], v236 offset:32
	ds_read_b64_tr_b16 v[94:95], v236 offset:448
	ds_read_b64_tr_b16 v[90:91], v236 offset:480
	v_mov_b32_e32 v81, 0
	v_mov_b32_e32 v82, 0
	v_mov_b32_e32 v83, 0
	s_and_saveexec_b64 s[0:1], s[10:11]
	s_add_i32 s6, 0, 0x24b00
	v_add_u32_e32 v5, s6, v197
	ds_read_b128 v[80:83], v5 offset:192
	s_or_b64 exec, exec, s[0:1]
	s_waitcnt lgkmcnt(1)
	v_mfma_f32_16x16x32_bf16 v[76:79], v[92:95], v[118:121], v[76:79]
	v_mfma_f32_16x16x32_bf16 v[96:99], v[92:95], v[114:117], v[98:101]
	s_waitcnt lgkmcnt(0)
	v_mfma_f32_16x16x32_bf16 v[92:95], v[88:91], v[118:121], v[102:105]
	v_mfma_f32_16x16x32_bf16 v[88:91], v[88:91], v[114:117], v[84:87]
	v_mfma_f32_16x16x32_bf16 v[84:87], v[80:83], v[118:121], v[106:109]
	v_mfma_f32_16x16x32_bf16 v[80:83], v[80:83], v[114:117], v[110:113]
	s_nop 1
	v_cvt_pk_bf16_f32 v6, v76, v77
	v_cvt_pk_bf16_f32 v7, v78, v79
	s_nop 0
	v_cvt_pk_bf16_f32 v102, v92, v93
	v_cvt_pk_bf16_f32 v103, v94, v95
	s_barrier
	v_cvt_pk_bf16_f32 v100, v96, v97
	v_cvt_pk_bf16_f32 v101, v98, v99
	ds_write2_b64 v237, v[6:7], v[102:103] offset1:4
	v_cvt_pk_bf16_f32 v6, v88, v89
	v_cvt_pk_bf16_f32 v7, v90, v91
	ds_write2_b64 v237, v[100:101], v[6:7] offset0:224 offset1:228
	s_and_saveexec_b64 s[0:1], s[14:15]
	s_xor_b64 s[0:1], exec, s[0:1]
	s_andn2_saveexec_b64 s[0:1], s[0:1]
	s_cbranch_execz .LBB0_249
	v_cvt_pk_bf16_f32 v6, v84, s0
	v_cvt_pk_bf16_f32 v5, v80, s0
	ds_write_b16 v238, v6
	ds_write_b16 v239, v5
	s_branch .LBB0_249

; __device__ __forceinline__ void attn_load(const bf16_t* R1, const AttnItem& a, int tid, u32x4 (&kr)[8], u32x4 (&vr)[8]) {
;     const int lg = 2 * a.g;
;     ...
;     const bf16_t* Kq = (const bf16_t*)((const unsigned char*)R1 + R1_KA) + seq; const bf16_t* Vq = (const bf16_t*)((const unsigned char*)R1 + R1_VA) + seq;
;     const int row = tid >> 1, pv = tid & 1; const int jk = a.blk * 128 - 128 + row;
;     const u32x4 z = (u32x4){0u, 0u, 0u, 0u};
;     if (jk >= 0) { const bf16_t* src = Kq + (size_t)jk * 128; kr[0] = *(const u32x4*)(src + 8 * pv); kr[1] = *(const u32x4*)(src + 16 + 8 * pv); } else { kr[0] = z; kr[1] = z; }
; #pragma unroll
;     for (int i = 0; i < 6; ++i) {
;         const int task = tid + 512 * i; const int row2 = task / 12, v = 4 + task % 12; const int jk2 = a.blk * 128 - 128 + row2;
;         kr[2 + i] = (jk2 >= 0) ? *(const u32x4*)(Kq + (size_t)jk2 * 128 + v * 8) : z;
; __device__ __forceinline__ void p4_attn(const Params& p, LAS unsigned char* lds, const int dummy) {
;     ...
;         {
;             bf16_t* qsrc = R1 + tq * QZ_LD + qcol;
; #pragma unroll
;             for (int kk = 0; kk < 4; ++kk) {
;                 const u32x4 av = *(const u32x4*)(qsrc + 32 * kk + 8 * q);
;                 float x[8]; unpack8(av, x);
;                 if (kk == 0) {
;                     const int fi = 8 * (q & 1);
;                     const float4 ca = *(const float4*)(RC + posq * 16 + fi), cb = *(const float4*)(RC + posq * 16 + fi + 4);
;                     const float4 sa = *(const float4*)(RS + posq * 16 + fi), sb = *(const float4*)(RS + posq * 16 + fi + 4);
;                     const float cc[8] = {ca.x, ca.y, ca.z, ca.w, cb.x, cb.y, cb.z, cb.w}, sn[8] = {sa.x, sa.y, sa.z, sa.w, sb.x, sb.y, sb.z, sb.w};
; #pragma unroll
;                     for (int e = 0; e < 8; ++e) { const float xo = __shfl_xor(x[e], 32); x[e] = (q < 2) ? (x[e] * cc[e] - xo * sn[e]) : (x[e] * cc[e] + xo * sn[e]); }
;                 }
; #pragma unroll
;                 for (int e = 0; e < 8; ++e) x[e] *= QSCALE;
;                 qf[kk] = __builtin_bit_cast(bf16x8, pack8(x));
;             }
;         }
;         __syncthreads();
;         if (it + (int)gridDim.x < 1536) { const AttnItem an = attn_item(it + gridDim.x); attn_load(R1, an, tid, kr, vr); }
.LBB0_612:
	s_waitcnt vmcnt(4) lgkmcnt(2)
	v_pk_mul_f32 v[84:85], v[84:85], v[104:105]
	s_waitcnt vmcnt(3)
	v_pk_mul_f32 v[38:39], v[92:93], v[110:111]
	v_cndmask_b32_e64 v85, v85, -v85, s[2:3]
	v_cndmask_b32_e64 v84, v84, -v84, s[2:3]
	v_pk_fma_f32 v[80:81], v[80:81], v[98:99], v[84:85]
	v_cndmask_b32_e64 v39, v39, -v39, s[2:3]
	v_cndmask_b32_e64 v38, v38, -v38, s[2:3]
	v_pk_mul_f32 v[84:85], v[80:81], s[84:85] op_sel_hi:[1,0]
	s_waitcnt lgkmcnt(0)
	v_pk_mul_f32 v[80:81], v[86:87], v[100:101]
	v_pk_fma_f32 v[38:39], v[88:89], v[106:107], v[38:39]
	v_cndmask_b32_e64 v81, v81, -v81, s[2:3]
	v_cndmask_b32_e64 v80, v80, -v80, s[2:3]
	v_pk_mul_f32 v[38:39], v[38:39], s[84:85] op_sel_hi:[1,0]
	v_pk_mul_f32 v[88:89], v[94:95], v[108:109]
	v_pk_fma_f32 v[80:81], v[82:83], v[96:97], v[80:81]
	v_cndmask_b32_e64 v89, v89, -v89, s[2:3]
	v_cndmask_b32_e64 v88, v88, -v88, s[2:3]
	v_pk_mul_f32 v[86:87], v[80:81], s[84:85] op_sel_hi:[1,0]
	v_cvt_pk_bf16_f32 v80, v38, v39
	s_waitcnt vmcnt(2)
	v_lshlrev_b32_e32 v38, 16, v76
	v_and_b32_e32 v39, 0xffff0000, v76
	v_lshlrev_b32_e32 v76, 16, v77
	v_and_b32_e32 v77, 0xffff0000, v77
	v_pk_fma_f32 v[88:89], v[90:91], v[102:103], v[88:89]
	v_cvt_pk_bf16_f32 v82, v84, v85
	v_pk_mul_f32 v[84:85], v[76:77], s[84:85] op_sel_hi:[1,0]
	v_lshlrev_b32_e32 v76, 16, v78
	v_and_b32_e32 v77, 0xffff0000, v78
	v_pk_mul_f32 v[88:89], v[88:89], s[84:85] op_sel_hi:[1,0]
	v_cvt_pk_bf16_f32 v83, v86, v87
	v_pk_mul_f32 v[38:39], v[38:39], s[84:85] op_sel_hi:[1,0]
	v_pk_mul_f32 v[86:87], v[76:77], s[84:85] op_sel_hi:[1,0]
	v_lshlrev_b32_e32 v76, 16, v79
	v_and_b32_e32 v77, 0xffff0000, v79
	v_cvt_pk_bf16_f32 v81, v88, v89
	v_pk_mul_f32 v[88:89], v[76:77], s[84:85] op_sel_hi:[1,0]
	v_cvt_pk_bf16_f32 v76, v38, v39
	s_waitcnt vmcnt(1)
	v_lshlrev_b32_e32 v38, 16, v72
	v_and_b32_e32 v39, 0xffff0000, v72
	v_lshlrev_b32_e32 v72, 16, v73
	v_and_b32_e32 v73, 0xffff0000, v73
	v_cvt_pk_bf16_f32 v77, v84, v85
	v_pk_mul_f32 v[38:39], v[38:39], s[84:85] op_sel_hi:[1,0]
	v_pk_mul_f32 v[72:73], v[72:73], s[84:85] op_sel_hi:[1,0]
	v_lshlrev_b32_e32 v84, 16, v74
	v_and_b32_e32 v85, 0xffff0000, v74
	v_cvt_pk_bf16_f32 v78, v86, v87
	v_pk_mul_f32 v[86:87], v[84:85], s[84:85] op_sel_hi:[1,0]
	v_lshlrev_b32_e32 v74, 16, v75
	v_and_b32_e32 v75, 0xffff0000, v75
	v_cvt_pk_bf16_f32 v84, v38, v39
	v_cvt_pk_bf16_f32 v85, v72, v73
	s_waitcnt vmcnt(0)
	s_and_b64 vcc, exec, s[86:87]
	s_cbranch_vccnz .Lattn_pf_done
	s_ashr_i32 s0, s8, 6
	s_mul_hi_i32 s5, s0, 0x55555556
	s_lshr_b32 s6, s5, 31
	s_add_i32 s5, s5, s6
	s_mul_i32 s5, s5, 3
	s_sub_i32 s0, s0, s5
	s_mul_hi_i32 s5, s8, 0x2aaaaaab
	s_lshr_b32 s6, s5, 31
	s_ashr_i32 s5, s5, 5
	s_add_i32 s5, s5, s6
	s_bfe_u32 s4, s8, 0x20004
	s_lshl_b32 s6, s0, 1
	s_lshl_b32 s5, s5, 2
	s_and_b32 s1, s8, 15
	s_sub_i32 s12, 4, s6
	s_or_b32 s4, s5, s4
	s_lshr_b32 s12, s1, s12
	s_lshl_b32 s4, s4, s6
	s_lshr_b32 s7, 16, s6
	s_add_i32 s4, s12, s4
	s_lshr_b32 s5, 0x800, s6
	s_add_i32 s7, s7, -1
	s_mul_i32 s4, s4, s5
	s_and_b32 s7, s7, s1
	s_ashr_i32 s1, s0, 31
	s_ashr_i32 s5, s4, 31
	s_lshl_b64 s[0:1], s[0:1], 23
	s_lshl_b64 s[4:5], s[4:5], 7
	s_add_u32 s0, s4, s0
	s_addc_u32 s1, s5, s1
	s_lshl_b64 s[4:5], s[0:1], 1
	s_add_u32 s82, s14, s4
	s_addc_u32 s83, s15, s5
	s_lshl_b32 s12, s7, 7
	v_add_u32_e32 v20, s12, v144
	v_mov_b32_e32 v0, 0
	v_cmp_lt_i32_e32 vcc, -1, v20
	v_mov_b32_e32 v1, v0
	v_mov_b32_e32 v2, v0
	v_mov_b32_e32 v3, v0
	v_mov_b32_e32 v4, v0
	v_mov_b32_e32 v5, v0
	v_mov_b32_e32 v6, v0
	v_mov_b32_e32 v7, v0
	s_and_saveexec_b64 s[0:1], vcc
	s_cbranch_execz .LBB0_597
	v_mov_b32_e32 v21, v36
	v_lshlrev_b64 v[0:1], 8, v[20:21]
	v_lshl_add_u64 v[0:1], s[82:83], 0, v[0:1]
	v_lshlrev_b32_e32 v2, 1, v130
	v_mov_b32_e32 v3, v36
	v_lshl_add_u64 v[4:5], v[0:1], 0, v[2:3]
	global_load_dwordx4 v[0:3], v[4:5], off
	s_nop 0
	global_load_dwordx4 v[4:7], v[4:5], off offset:32

; #define LAS __attribute__((address_space(3)))
; __device__ __forceinline__ void p4_attn(const Params& p, LAS unsigned char* lds, const int dummy) {
;     ...
; #pragma unroll
;                 for (int e = 0; e < 8; ++e) x[e] *= QSCALE;
;                 qf[kk] = __builtin_bit_cast(bf16x8, pack8(x));
;             }
;         }
;         __syncthreads();
;         if (it + (int)gridDim.x < 1536) { const AttnItem an = attn_item(it + gridDim.x); attn_load(R1, an, tid, kr, vr); }
;         const int ilo = (blk == 0) ? 8 - wid : 0;
;         f32x4 sT[9];
; #pragma unroll
;         for (int i = 0; i < 9; ++i) sT[i] = (f32x4){0.f, 0.f, 0.f, 0.f};
; #pragma unroll
;         for (int gi = 0; gi < 3; ++gi) {
;             if (3 * gi + 2 >= ilo) {
;                 bf16x8 ka[3][4];
; #pragma unroll
;                 for (int i3 = 0; i3 < 3; ++i3)
; #pragma unroll
;                     for (int kk = 0; kk < 4; ++kk) ka[i3][kk] = *(const LAS bf16x8*)(KA + (16 * (wid + 3 * gi + i3) + r) * KA_STRIDE + (32 * kk + 8 * q) * 2);
;                 __builtin_amdgcn_sched_barrier(0);
; #pragma unroll
;                 for (int kk = 0; kk < 4; ++kk)
; #pragma unroll
;                     for (int i3 = 0; i3 < 3; ++i3) sT[3 * gi + i3] = __builtin_amdgcn_mfma_f32_16x16x32_bf16(ka[i3][kk], qf[kk], sT[3 * gi + i3], 0, 0, 0);
;                 __builtin_amdgcn_sched_barrier(0);
.Lattn_pf_done:
	v_lshlrev_b32_e32 v38, 16, v68
	v_and_b32_e32 v39, 0xffff0000, v68
	v_lshlrev_b32_e32 v68, 16, v69
	v_and_b32_e32 v69, 0xffff0000, v69
	v_lshlrev_b32_e32 v72, 16, v70
	v_and_b32_e32 v73, 0xffff0000, v70
	v_lshlrev_b32_e32 v70, 16, v71
	v_and_b32_e32 v71, 0xffff0000, v71
	s_cmp_eq_u32 s81, 0
	v_pk_mul_f32 v[74:75], v[74:75], s[84:85] op_sel_hi:[1,0]
	v_pk_mul_f32 v[38:39], v[38:39], s[84:85] op_sel_hi:[1,0]
	v_pk_mul_f32 v[68:69], v[68:69], s[84:85] op_sel_hi:[1,0]
	v_pk_mul_f32 v[72:73], v[72:73], s[84:85] op_sel_hi:[1,0]
	v_pk_mul_f32 v[70:71], v[70:71], s[84:85] op_sel_hi:[1,0]
	s_cselect_b32 s6, s18, 0
	v_cvt_pk_bf16_f32 v79, v88, v89
	v_cvt_pk_bf16_f32 v86, v86, v87
	v_cvt_pk_bf16_f32 v87, v74, v75
	v_cvt_pk_bf16_f32 v92, v38, v39
	v_cvt_pk_bf16_f32 v93, v68, v69
	v_cvt_pk_bf16_f32 v94, v72, v73
	v_cvt_pk_bf16_f32 v95, v70, v71
	v_mov_b32_e32 v72, 0
	s_cmp_gt_i32 s6, 2
	v_mov_b32_e32 v73, 0
	v_mov_b32_e32 v74, 0
	v_mov_b32_e32 v75, 0
	v_mov_b32_e32 v88, 0
	v_mov_b32_e32 v89, 0
	v_mov_b32_e32 v90, 0
	v_mov_b32_e32 v91, 0
	v_mov_b32_e32 v96, 0
	v_mov_b32_e32 v97, 0
	v_mov_b32_e32 v98, 0
	v_mov_b32_e32 v99, 0
	s_cbranch_scc1 .LBB0_614
	ds_read_b128 v[68:71], v180
	ds_read_b128 v[72:75], v180 offset:64
	ds_read_b128 v[88:91], v180 offset:128
	ds_read_b128 v[96:99], v180 offset:192
	ds_read_b128 v[100:103], v181
	ds_read_b128 v[104:107], v181 offset:64
	ds_read_b128 v[108:111], v181 offset:128
	ds_read_b128 v[202:205], v181 offset:192
	ds_read_b128 v[206:209], v182
	ds_read_b128 v[214:217], v182 offset:64
	ds_read_b128 v[218:221], v182 offset:128
	ds_read_b128 v[222:225], v182 offset:192
	s_waitcnt lgkmcnt(11)
	v_mfma_f32_16x16x32_bf16 v[68:71], v[68:71], v[80:83], 0
	s_waitcnt lgkmcnt(7)
	v_mfma_f32_16x16x32_bf16 v[100:103], v[100:103], v[80:83], 0
	s_waitcnt lgkmcnt(3)
	v_mfma_f32_16x16x32_bf16 v[206:209], v[206:209], v[80:83], 0
	v_mfma_f32_16x16x32_bf16 v[68:71], v[72:75], v[76:79], v[68:71]
	v_mfma_f32_16x16x32_bf16 v[72:75], v[104:107], v[76:79], v[100:103]
	s_waitcnt lgkmcnt(2)
	v_mfma_f32_16x16x32_bf16 v[100:103], v[214:217], v[76:79], v[206:209]
	v_mfma_f32_16x16x32_bf16 v[68:71], v[88:91], v[84:87], v[68:71]
	v_mfma_f32_16x16x32_bf16 v[72:75], v[108:111], v[84:87], v[72:75]
	s_waitcnt lgkmcnt(1)
	v_mfma_f32_16x16x32_bf16 v[100:103], v[218:221], v[84:87], v[100:103]
	v_mfma_f32_16x16x32_bf16 v[96:99], v[96:99], v[92:95], v[68:71]
	v_mfma_f32_16x16x32_bf16 v[88:91], v[202:205], v[92:95], v[72:75]
	s_waitcnt lgkmcnt(0)
	v_mfma_f32_16x16x32_bf16 v[72:75], v[222:225], v[92:95], v[100:103]

; __global__ void __launch_bounds__(512, 2) mega_fwd(Params p) {
;     extern __shared__ __attribute__((aligned(16))) unsigned char lds_raw[];
	.amdhsa_kernel _Z8mega_fwd6Params
		.amdhsa_group_segment_fixed_size 0
		.amdhsa_private_segment_fixed_size 0
		.amdhsa_kernarg_size 368
		.amdhsa_user_sgpr_count 2
		.amdhsa_user_sgpr_dispatch_ptr 0
		.amdhsa_user_sgpr_queue_ptr 0
		.amdhsa_user_sgpr_kernarg_segment_ptr 1
		.amdhsa_user_sgpr_dispatch_id 0
		.amdhsa_user_sgpr_kernarg_preload_length 0
		.amdhsa_user_sgpr_kernarg_preload_offset 0
		.amdhsa_user_sgpr_private_segment_size 0
		.amdhsa_uses_dynamic_stack 0
		.amdhsa_enable_private_segment 0
		.amdhsa_system_sgpr_workgroup_id_x 1
		.amdhsa_system_sgpr_workgroup_id_y 0
		.amdhsa_system_sgpr_workgroup_id_z 0
		.amdhsa_system_sgpr_workgroup_info 0
		.amdhsa_system_vgpr_workitem_id 2
		.amdhsa_next_free_vgpr 255
		.amdhsa_next_free_sgpr 102
		.amdhsa_accum_offset 256
		.amdhsa_reserve_vcc 1
		.amdhsa_float_round_mode_32 0
		.amdhsa_float_round_mode_16_64 0
		.amdhsa_float_denorm_mode_32 3
		.amdhsa_float_denorm_mode_16_64 3
		.amdhsa_dx10_clamp 1
		.amdhsa_ieee_mode 1
		.amdhsa_fp16_overflow 0
		.amdhsa_tg_split 0
		.amdhsa_exception_fp_ieee_invalid_op 0
		.amdhsa_exception_fp_denorm_src 0
		.amdhsa_exception_fp_ieee_div_zero 0
		.amdhsa_exception_fp_ieee_overflow 0
		.amdhsa_exception_fp_ieee_underflow 0
		.amdhsa_exception_fp_ieee_inexact 0
		.amdhsa_exception_int_div_zero 0
	.end_amdhsa_kernel

; __global__ void __launch_bounds__(512, 2) mega_fwd(Params p) {
;     extern __shared__ __attribute__((aligned(16))) unsigned char lds_raw[];
amdhsa.kernels:
  - .agpr_count:     0
    .args:
      - .offset:         0
        .size:           112
        .value_kind:     by_value
      - .offset:         112
        .size:           4
        .value_kind:     hidden_block_count_x
      - .offset:         116
        .size:           4
        .value_kind:     hidden_block_count_y
      - .offset:         120
        .size:           4
        .value_kind:     hidden_block_count_z
      - .offset:         124
        .size:           2
        .value_kind:     hidden_group_size_x
      - .offset:         126
        .size:           2
        .value_kind:     hidden_group_size_y
      - .offset:         128
        .size:           2
        .value_kind:     hidden_group_size_z
      - .offset:         130
        .size:           2
        .value_kind:     hidden_remainder_x
      - .offset:         132
        .size:           2
        .value_kind:     hidden_remainder_y
      - .offset:         134
        .size:           2
        .value_kind:     hidden_remainder_z
      - .offset:         152
        .size:           8
        .value_kind:     hidden_global_offset_x
      - .offset:         160
        .size:           8
        .value_kind:     hidden_global_offset_y
      - .offset:         168
        .size:           8
        .value_kind:     hidden_global_offset_z
      - .offset:         176
        .size:           2
        .value_kind:     hidden_grid_dims
      - .offset:         200
        .size:           8
        .value_kind:     hidden_multigrid_sync_arg
      - .offset:         232
        .size:           4
        .value_kind:     hidden_dynamic_lds_size
    .group_segment_fixed_size: 0
    .kernarg_segment_align: 8
    .kernarg_segment_size: 368
    .language:       OpenCL C
    .language_version:
      - 2
      - 0
    .max_flat_workgroup_size: 512
    .name:           _Z8mega_fwd6Params
    .private_segment_fixed_size: 0
    .sgpr_count:     108
    .sgpr_spill_count: 86
    .symbol:         _Z8mega_fwd6Params.kd
    .uniform_work_group_size: 1
    .uses_dynamic_stack: false
    .vgpr_count:     255
    .vgpr_spill_count: 0
    .wavefront_size: 64
